# v82 plus retention S-section second-tile K-fragment reads issued right after the first tile's MFMAs
# baseline (speedup 1.0000x reference)
; #define LAS __attribute__((address_space(3)))
; #define LBAR() do { asm volatile("s_waitcnt lgkmcnt(0)" ::: "memory"); __builtin_amdgcn_s_barrier(); asm volatile("" ::: "memory"); } while (0)
; __device__ __forceinline__ unsigned pk2(float lo, float hi) { return pg8::cvt_pk_bf16(lo, hi); }
; __device__ __forceinline__ f32x4 mfma16(bf16x8 a, bf16x8 b, f32x4 c) { return __builtin_amdgcn_mfma_f32_16x16x32_bf16(a, b, c, 0, 0, 0); }
; __device__ __forceinline__ void retention_unit(LAS unsigned char* lds, const Ptrs& P, int b, int h, int tid) {
;     ...
;         if (n < 32) {
; #pragma unroll
;             for (int j2 = 0; j2 < 2; ++j2) {
;                 const int jt = (w & 1) * 2 + j2; f32x4 a4 = (f32x4){0.f, 0.f, 0.f, 0.f};
; #pragma unroll
;                 for (int ks = 0; ks < 2; ++ks) {
;                     const bf16x8 qf = *(const LAS bf16x8*)(Qs + (16 * it3 + fr) * S72 + 32 * ks + 8 * fq), kf = *(const LAS bf16x8*)(Ks + (16 * jt + fr) * S72 + 32 * ks + 8 * fq);
;                     a4 = mfma16(kf, qf, a4); }
;                 a4 = a4 * decv[j2];
;                 v2u pw; pw.x = pk2(a4[0], a4[1]); pw.y = pk2(a4[2], a4[3]);
;                 *(LAS v2u*)(Ss + (16 * it3 + fr) * S72 + 16 * jt + 4 * fq) = pw;
;             }
;         }
;         LBAR();
;         if (n >= 1) {
; #pragma unroll
;             for (int it = 0; it < 4; ++it) { const int i = 16 * it + fr; const float mean = stat[i * 2], rstd = stat[i * 2 + 1]; const v2u sg = sgr[it];
;                 const f32x4 y = (op[it] - mean) * rstd * gng4 * (f32x4){bflo(sg.x), bfhi(sg.x), bflo(sg.y), bfhi(sg.y)};
;                 v2u pw; pw.x = pk2(y[0], y[1]); pw.y = pk2(y[2], y[3]);
;                 *(v2u*)(gol + ((size_t)(n - 1) * 64 + 16 * it) * 1024) = pw; }
;         }
;         if (n < 32) {
;             f32x4 o[4]; bf16x8 bst[2], bv[2];
; #pragma unroll
;             for (int ks = 0; ks < 2; ++ks) { bst[ks] = *(const LAS bf16x8*)(St + (16 * w + fr) * S72 + 32 * ks + 8 * fq); bv[ks] = tr_frag(bufc + ROFF_V, S144 * 2, w, ks, fq, fr); }
; #pragma unroll
;             for (int it = 0; it < 4; ++it) { o[it] = (f32x4){0.f, 0.f, 0.f, 0.f};
; #pragma unroll
;                 for (int ks = 0; ks < 2; ++ks) { const bf16x8 qf = *(const LAS bf16x8*)(Qs + (16 * it + fr) * S72 + 32 * ks + 8 * fq); o[it] = mfma16(bst[ks], qf, o[it]); }
.LBB0_657:
	s_or_b64 exec, exec, s[18:19]
	v_lshl_add_u32 v60, v155, 1, s90
	s_waitcnt lgkmcnt(0)
	v_add_u32_e32 v60, v60, v178
	v_and_b32_e32 v61, 0xffff0000, v54
	v_add_u32_e32 v75, 0, v160
	v_add_u32_e32 v143, 0x21400, v75
	v_lshl_add_u64 v[120:121], s[26:27], 0, v[114:115]
	v_add3_u32 v204, s90, v82, v169
	s_waitcnt lgkmcnt(1)
	v_mfma_f32_16x16x32_bf16 v[56:59], v[216:219], v[188:191], 0
	s_add_i32 s18, s90, s87
	v_lshlrev_b32_e32 v200, 16, v122
	v_and_b32_e32 v201, 0xffff0000, v122
	s_waitcnt lgkmcnt(0)
	v_mfma_f32_16x16x32_bf16 v[56:59], v[220:223], v[192:195], v[56:59]
	ds_read_b128 v[224:227], v60 offset:9216
	ds_read_b128 v[228:231], v60 offset:9280
	v_lshlrev_b32_e32 v122, 16, v123
	v_and_b32_e32 v123, 0xffff0000, v123
	v_add3_u32 v212, s90, v162, v170
	v_mov_b32_e32 v75, v74
	v_pk_mul_f32 v[18:19], v[74:75], v[18:19]
	s_nop 2
	v_pk_mul_f32 v[58:59], v[100:101], v[58:59]
	v_pk_mul_f32 v[56:57], v[98:99], v[56:57]
	v_pk_mul_f32 v[16:17], v[76:77], v[16:17]
	v_cvt_pk_bf16_f32 v56, v56, v57
	v_cvt_pk_bf16_f32 v57, v58, v59
	ds_write_b64 v177, v[56:57]
	s_waitcnt lgkmcnt(2)
	v_mfma_f32_16x16x32_bf16 v[56:59], v[224:227], v[188:191], 0
	v_lshlrev_b32_e32 v60, 16, v54
	v_lshlrev_b32_e32 v188, 16, v55
	v_and_b32_e32 v189, 0xffff0000, v55
	s_waitcnt lgkmcnt(1)
	v_mfma_f32_16x16x32_bf16 v[54:57], v[228:231], v[192:195], v[56:59]
	ds_read_b128 v[216:219], v204
	ds_read_b128 v[220:223], v204 offset:64
	ds_read_b128 v[224:227], v204 offset:2304
	ds_read_b128 v[228:231], v204 offset:2368
	ds_read_b128 v[232:235], v204 offset:4608
	ds_read_b128 v[236:239], v204 offset:4672
	ds_read_b128 v[240:243], v204 offset:6912
	ds_read_b128 v[244:247], v204 offset:6976
	v_mul_f32_e64 v14, v74, v14
	v_mul_f32_e64 v15, v75, v15
	v_pk_mul_f32 v[12:13], v[76:77], v[12:13]
	v_pk_mul_f32 v[10:11], v[74:75], v[10:11]
	v_add_co_u32_e32 v58, vcc, s66, v120
	v_pk_mul_f32 v[8:9], v[76:77], v[8:9]
	s_nop 1
	v_pk_mul_f32 v[56:57], v[94:95], v[56:57]
	v_pk_mul_f32 v[54:55], v[92:93], v[54:55]
	v_addc_co_u32_e32 v59, vcc, 0, v121, vcc
	v_cvt_pk_bf16_f32 v54, v54, v55
	v_cvt_pk_bf16_f32 v55, v56, v57
	ds_write_b64 v142, v[54:55]
	s_waitcnt lgkmcnt(0)
	s_barrier
	ds_read2_b64 v[54:57], v143 offset1:16
	ds_read_b128 v[184:187], v137
	v_pk_mul_f32 v[6:7], v[74:75], v[6:7]
	v_pk_mul_f32 v[4:5], v[76:77], v[4:5]
	v_lshl_add_u64 v[110:111], v[110:111], 0, s[8:9]
	s_waitcnt lgkmcnt(1)
	v_sub_f32_e32 v41, v41, v54
	v_sub_f32_e32 v40, v40, v54
	v_sub_f32_e32 v43, v43, v54
	v_sub_f32_e32 v42, v42, v54
	v_pk_mul_f32 v[42:43], v[54:55], v[42:43] op_sel:[1,0]
	v_pk_mul_f32 v[40:41], v[54:55], v[40:41] op_sel:[1,0]
	v_pk_mul_f32 v[42:43], v[2:3], v[42:43]
	v_pk_mul_f32 v[40:41], v[0:1], v[40:41]
	v_pk_mul_f32 v[42:43], v[42:43], v[188:189]
	v_pk_mul_f32 v[40:41], v[40:41], v[60:61]
	v_sub_f32_e32 v45, v45, v56
	v_cvt_pk_bf16_f32 v40, v40, v41
	v_cvt_pk_bf16_f32 v41, v42, v43
	v_sub_f32_e32 v44, v44, v56
	global_store_dwordx2 v[58:59], v[40:41], off
	v_sub_f32_e32 v41, v47, v56
	v_sub_f32_e32 v40, v46, v56
	v_pk_mul_f32 v[40:41], v[56:57], v[40:41] op_sel:[1,0]
	v_pk_mul_f32 v[42:43], v[56:57], v[44:45] op_sel:[1,0]
	ds_read2_b64 v[54:57], v143 offset0:32 offset1:48
	v_pk_mul_f32 v[42:43], v[0:1], v[42:43]
	v_pk_mul_f32 v[40:41], v[2:3], v[40:41]
	v_lshlrev_b32_e32 v44, 16, v52
	v_and_b32_e32 v45, 0xffff0000, v52
	v_lshlrev_b32_e32 v46, 16, v53
	v_and_b32_e32 v47, 0xffff0000, v53
	v_pk_mul_f32 v[40:41], v[40:41], v[46:47]
	v_pk_mul_f32 v[42:43], v[42:43], v[44:45]
	ds_read_b128 v[188:191], v137 offset:64
	v_cvt_pk_bf16_f32 v42, v42, v43
	v_cvt_pk_bf16_f32 v43, v40, v41
	v_add_co_u32_e32 v40, vcc, s67, v120
	s_nop 0
	v_addc_co_u32_e32 v41, vcc, 0, v121, vcc
	global_store_dwordx2 v[40:41], v[42:43], off
	s_waitcnt lgkmcnt(1)
	v_sub_f32_e32 v41, v49, v54
	v_sub_f32_e32 v40, v48, v54
	v_sub_f32_e32 v43, v51, v54
	v_sub_f32_e32 v42, v50, v54
	v_pk_mul_f32 v[40:41], v[54:55], v[40:41] op_sel:[1,0]
	v_pk_mul_f32 v[192:193], v[54:55], v[42:43] op_sel:[1,0]
	v_pk_mul_f32 v[196:197], v[0:1], v[40:41]
	s_waitcnt lgkmcnt(0)
	v_mfma_f32_16x16x32_bf16 v[40:43], v[184:187], v[216:219], 0
	v_add3_u32 v48, s18, v162, v168
	ds_read_b64_tr_b16 v[58:59], v48 offset:27648
	ds_read_b64_tr_b16 v[60:61], v48 offset:28800
	ds_read_b64_tr_b16 v[52:53], v48 offset:36864
	ds_read_b64_tr_b16 v[54:55], v48 offset:38016
	ds_read_b128 v[48:51], v129
	v_pk_mul_f32 v[192:193], v[2:3], v[192:193]
	v_mfma_f32_16x16x32_bf16 v[40:43], v[188:191], v[220:223], v[40:43]
	ds_read_b128 v[44:47], v129 offset:64
	v_pk_mul_f32 v[122:123], v[192:193], v[122:123]
	ds_read_b128 v[192:195], v129 offset:2304
	v_lshl_add_u64 v[112:113], v[112:113], 0, s[12:13]
	v_lshl_add_u64 v[114:115], v[114:115], 0, s[14:15]
	s_nop 2
	v_pk_mul_f32 v[42:43], v[108:109], v[42:43]
	v_pk_mul_f32 v[40:41], v[90:91], v[40:41]
	s_cmp_lg_u32 s89, 30
	v_lshl_add_u64 v[116:117], v[116:117], 0, s[12:13]
	s_waitcnt lgkmcnt(2)
	v_mfma_f32_16x16x32_bf16 v[40:43], v[58:61], v[48:51], v[40:43]
	s_waitcnt lgkmcnt(1)
	v_mfma_f32_16x16x32_bf16 v[40:43], v[52:55], v[44:47], v[40:43]
	s_waitcnt lgkmcnt(0)
	v_mfma_f32_16x16x32_bf16 v[48:51], v[184:187], v[224:227], 0
	s_waitcnt lgkmcnt(0)
; #define LAS __attribute__((address_space(3)))
; __device__ __forceinline__ unsigned pk2(float lo, float hi) { return pg8::cvt_pk_bf16(lo, hi); }
; __device__ __forceinline__ f32x4 mfma16(bf16x8 a, bf16x8 b, f32x4 c) { return __builtin_amdgcn_mfma_f32_16x16x32_bf16(a, b, c, 0, 0, 0); }
; __device__ __forceinline__ void retention_unit(LAS unsigned char* lds, const Ptrs& P, int b, int h, int tid) {
;     ...
;         if (n < 32) {
;             f32x4 o[4]; bf16x8 bst[2], bv[2];
; #pragma unroll
;             for (int ks = 0; ks < 2; ++ks) { bst[ks] = *(const LAS bf16x8*)(St + (16 * w + fr) * S72 + 32 * ks + 8 * fq); bv[ks] = tr_frag(bufc + ROFF_V, S144 * 2, w, ks, fq, fr); }
; #pragma unroll
;             for (int it = 0; it < 4; ++it) { o[it] = (f32x4){0.f, 0.f, 0.f, 0.f};
; #pragma unroll
;                 for (int ks = 0; ks < 2; ++ks) { const bf16x8 qf = *(const LAS bf16x8*)(Qs + (16 * it + fr) * S72 + 32 * ks + 8 * fq); o[it] = mfma16(bst[ks], qf, o[it]); }
;                 o[it] = o[it] * dqv[it];
; #pragma unroll
;                 for (int ks = 0; ks < 2; ++ks) { const bf16x8 sf = *(const LAS bf16x8*)(Ss + (16 * it + fr) * S72 + 32 * ks + 8 * fq); o[it] = mfma16(bv[ks], sf, o[it]); }
;             }
; #pragma unroll
;             for (int dt = 0; dt < 4; ++dt) { st[dt] = st[dt] * dch;
; #pragma unroll
;                 for (int ks = 0; ks < 2; ++ks) { const bf16x8 kf = tr_frag(bufc + ROFF_K2, S72 * 2, dt, ks, fq, fr); st[dt] = mfma16(kf, bv[ks], st[dt]); }
;                 v2u pw; pw.x = pk2(st[dt][0], st[dt][1]); pw.y = pk2(st[dt][2], st[dt][3]);
;                 *(LAS v2u*)(St + (16 * w + fr) * S72 + 16 * dt + 4 * fq) = pw; }
; #pragma unroll
;             for (int it = 0; it < 4; ++it) { const f32x4 v = o[it]; typedef float f32x2 __attribute__((ext_vector_type(2)));
;                 *(LAS f32x2*)(part + ((16 * it + fr) * 32 + w * 4 + fq) * 2) = (f32x2){(v[0] + v[1]) + (v[2] + v[3]), (v[0] * v[0] + v[1] * v[1]) + (v[2] * v[2] + v[3] * v[3])};
;                 op[it] = v; }
	v_mfma_f32_16x16x32_bf16 v[44:47], v[188:191], v[228:231], v[48:51]
	ds_read_b64_tr_b16 v[216:217], v212 offset:18432
	ds_read_b64_tr_b16 v[218:219], v212 offset:19008
	ds_read_b64_tr_b16 v[220:221], v212 offset:23040
	ds_read_b64_tr_b16 v[222:223], v212 offset:23616
	ds_read_b64_tr_b16 v[224:225], v212 offset:18464
	ds_read_b64_tr_b16 v[226:227], v212 offset:19040
	ds_read_b64_tr_b16 v[228:229], v212 offset:23072
	ds_read_b64_tr_b16 v[230:231], v212 offset:23648
	s_nop 5
	ds_read_b128 v[48:51], v129 offset:2368
	s_nop 0
	v_pk_mul_f32 v[46:47], v[106:107], v[46:47]
	v_pk_mul_f32 v[44:45], v[78:79], v[44:45]
	s_nop 1
	v_mfma_f32_16x16x32_bf16 v[44:47], v[58:61], v[192:195], v[44:47]
	v_mul_f32_e64 v192, v196, v200
	v_mul_f32_e64 v193, v197, v201
	ds_read_b128 v[200:203], v129 offset:4608
	v_cvt_pk_bf16_f32 v192, v192, v193
	s_waitcnt lgkmcnt(1)
	v_mfma_f32_16x16x32_bf16 v[44:47], v[52:55], v[48:51], v[44:47]
	v_cvt_pk_bf16_f32 v193, v122, v123
	v_add_co_u32_e32 v122, vcc, s68, v120
	v_sub_f32_e32 v197, v23, v56
	s_nop 0
	v_addc_co_u32_e32 v123, vcc, 0, v121, vcc
	global_store_dwordx2 v[122:123], v[192:193], off
	s_waitcnt lgkmcnt(0)
	v_mfma_f32_16x16x32_bf16 v[48:51], v[184:187], v[232:235], 0
	v_sub_f32_e32 v123, v21, v56
	v_sub_f32_e32 v122, v20, v56
	v_sub_f32_e32 v196, v22, v56
	s_waitcnt lgkmcnt(0)
	v_mfma_f32_16x16x32_bf16 v[48:51], v[188:191], v[236:239], v[48:51]
	ds_read_b64_tr_b16 v[232:233], v212 offset:18496
	ds_read_b64_tr_b16 v[234:235], v212 offset:19072
	ds_read_b64_tr_b16 v[236:237], v212 offset:23104
	ds_read_b64_tr_b16 v[238:239], v212 offset:23680
	ds_read_b128 v[192:195], v129 offset:4672
	v_pk_mul_f32 v[196:197], v[56:57], v[196:197] op_sel:[1,0]
	v_pk_mul_f32 v[56:57], v[56:57], v[122:123] op_sel:[1,0]
	v_pk_mul_f32 v[122:123], v[2:3], v[196:197]
	v_pk_mul_f32 v[56:57], v[0:1], v[56:57]
	s_nop 2
	v_pk_mul_f32 v[50:51], v[104:105], v[50:51]
	v_pk_mul_f32 v[48:49], v[86:87], v[48:49]
	v_lshlrev_b32_e32 v196, 16, v118
	v_and_b32_e32 v197, 0xffff0000, v118
	v_mfma_f32_16x16x32_bf16 v[48:51], v[58:61], v[200:203], v[48:51]
	s_waitcnt lgkmcnt(0)
	v_mfma_f32_16x16x32_bf16 v[16:19], v[216:219], v[58:61], v[16:19]
	s_waitcnt lgkmcnt(0)
	v_mfma_f32_16x16x32_bf16 v[16:19], v[220:223], v[52:55], v[16:19]
	v_mfma_f32_16x16x32_bf16 v[48:51], v[52:55], v[192:195], v[48:51]
	ds_read_b128 v[204:207], v129 offset:6912
	ds_read_b128 v[208:211], v129 offset:6976
	s_nop 2
	v_cvt_pk_bf16_f32 v20, v16, v17
	v_cvt_pk_bf16_f32 v21, v18, v19
	ds_write_b64 v132, v[20:21]
	s_waitcnt lgkmcnt(3)
	v_mfma_f32_16x16x32_bf16 v[184:187], v[184:187], v[240:243], 0
	s_waitcnt lgkmcnt(0)
	v_mfma_f32_16x16x32_bf16 v[12:15], v[224:227], v[58:61], v[12:15]
	s_waitcnt lgkmcnt(0)
	v_mfma_f32_16x16x32_bf16 v[12:15], v[228:231], v[52:55], v[12:15]
	v_mfma_f32_16x16x32_bf16 v[184:187], v[188:191], v[244:247], v[184:187]
	ds_read_b64_tr_b16 v[240:241], v212 offset:18528
	ds_read_b64_tr_b16 v[242:243], v212 offset:19104
	ds_read_b64_tr_b16 v[244:245], v212 offset:23136
	ds_read_b64_tr_b16 v[246:247], v212 offset:23712
	s_nop 6
	v_cvt_pk_bf16_f32 v20, v12, v13
	v_cvt_pk_bf16_f32 v21, v14, v15
	ds_write_b64 v132, v[20:21] offset:32
	s_waitcnt lgkmcnt(0)
	v_mfma_f32_16x16x32_bf16 v[8:11], v[232:235], v[58:61], v[8:11]
	v_mul_f32_e64 v186, v96, v186
	v_mul_f32_e64 v187, v97, v187
	v_pk_mul_f32 v[184:185], v[88:89], v[184:185]
	v_lshlrev_b32_e32 v20, 16, v119
	s_waitcnt lgkmcnt(0)
	v_mfma_f32_16x16x32_bf16 v[8:11], v[236:239], v[52:55], v[8:11]
	v_and_b32_e32 v21, 0xffff0000, v119
	v_pk_mul_f32 v[20:21], v[122:123], v[20:21]
	v_mfma_f32_16x16x32_bf16 v[184:187], v[58:61], v[204:207], v[184:187]
	s_nop 4
	v_cvt_pk_bf16_f32 v22, v8, v9
	v_cvt_pk_bf16_f32 v23, v10, v11
	ds_write_b64 v132, v[22:23] offset:64
	v_pk_mul_f32 v[22:23], v[56:57], v[196:197]
	v_cvt_pk_bf16_f32 v57, v20, v21
	v_cvt_pk_bf16_f32 v56, v22, v23
	v_mfma_f32_16x16x32_bf16 v[20:23], v[52:55], v[208:211], v[184:187]
	s_nop 2
	s_waitcnt lgkmcnt(0)
	v_mfma_f32_16x16x32_bf16 v[4:7], v[240:243], v[58:61], v[4:7]
	v_add_co_u32_e32 v58, vcc, s69, v120
	s_waitcnt lgkmcnt(0)
	v_mfma_f32_16x16x32_bf16 v[4:7], v[244:247], v[52:55], v[4:7]
	v_addc_co_u32_e32 v59, vcc, 0, v121, vcc
	global_store_dwordx2 v[58:59], v[56:57], off
	v_mul_f32_e32 v55, v41, v41
	v_mul_f32_e32 v57, v42, v42
	s_nop 3
	v_cvt_pk_bf16_f32 v52, v4, v5
	v_cvt_pk_bf16_f32 v53, v6, v7
	ds_write_b64 v132, v[52:53] offset:96
	v_mul_f32_e32 v53, v40, v40
	v_mul_f32_e32 v59, v43, v43
	v_mov_b32_e32 v52, v40
	v_mov_b32_e32 v54, v41
	v_mov_b32_e32 v56, v42
	v_mov_b32_e32 v58, v43
	v_pk_add_f32 v[52:53], v[52:53], v[54:55]
	v_pk_add_f32 v[54:55], v[56:57], v[58:59]
	v_mul_f32_e32 v57, v46, v46
	v_pk_add_f32 v[52:53], v[52:53], v[54:55]
	ds_write_b64 v133, v[52:53]
	v_mul_f32_e32 v53, v44, v44
	v_mul_f32_e32 v55, v45, v45
	v_mul_f32_e32 v59, v47, v47
	v_mov_b32_e32 v52, v44
	v_mov_b32_e32 v54, v45
	v_mov_b32_e32 v56, v46
	v_mov_b32_e32 v58, v47
	v_pk_add_f32 v[52:53], v[52:53], v[54:55]
	v_pk_add_f32 v[54:55], v[56:57], v[58:59]
	v_mul_f32_e32 v57, v50, v50
	v_pk_add_f32 v[52:53], v[52:53], v[54:55]
	ds_write_b64 v134, v[52:53]
	v_mul_f32_e32 v53, v48, v48
	v_mul_f32_e32 v55, v49, v49
	v_mul_f32_e32 v59, v51, v51
	v_mov_b32_e32 v52, v48
	v_mov_b32_e32 v54, v49
	v_mov_b32_e32 v56, v50
	v_mov_b32_e32 v58, v51
	v_pk_add_f32 v[52:53], v[52:53], v[54:55]
	v_pk_add_f32 v[54:55], v[56:57], v[58:59]
	v_mul_f32_e32 v57, v22, v22
	v_pk_add_f32 v[52:53], v[52:53], v[54:55]
	ds_write_b64 v135, v[52:53]
	v_mul_f32_e32 v53, v20, v20
	v_mul_f32_e32 v55, v21, v21
	v_mul_f32_e32 v59, v23, v23
	v_mov_b32_e32 v52, v20
	v_mov_b32_e32 v54, v21
	v_mov_b32_e32 v56, v22
	v_mov_b32_e32 v58, v23
	v_pk_add_f32 v[52:53], v[52:53], v[54:55]
	v_pk_add_f32 v[54:55], v[56:57], v[58:59]
	s_nop 0
	v_pk_add_f32 v[52:53], v[52:53], v[54:55]
	ds_write_b64 v136, v[52:53]
	s_cbranch_scc0 .LBB0_660
